# GEMM K-loop: removed the back-to-back s_setprio 0 / s_setprio 1 pair between the two 16-MFMA groups of each block
# baseline (speedup 1.0000x reference)
.LBB0_810:
	s_add_i32 s6, s28, -2
	s_add_u32 s7, s2, 0x100
	s_addc_u32 s8, s3, 0
	s_add_u32 s2, s4, 0x80
	s_addc_u32 s3, s5, 0
	s_mov_b32 s4, 0
	s_add_i32 s9, s4, 2
	s_add_u32 s21, s2, 0x80
	s_addc_u32 s5, s3, 0
	s_add_i32 s29, 0, 0x10000
	s_cmp_eq_u32 s6, s4
	s_cselect_b32 s5, s23, s5
	s_cselect_b32 s4, s22, s21
	v_add_u32_e32 v0, s29, v204
	s_cselect_b32 s31, s25, s8
	s_cselect_b32 s30, s24, s7
	s_add_i32 s21, 0, 0x14000
	ds_read_b128 v[130:133], v0
	ds_read_b128 v[134:137], v0 offset:1024
	ds_read_b128 v[138:141], v0 offset:2048
	ds_read_b128 v[142:145], v0 offset:3072
	v_add_u32_e32 v0, s21, v204
	ds_read_b128 v[146:149], v0
	ds_read_b128 v[160:163], v0 offset:1024
	ds_read_b128 v[164:167], v0 offset:2048
	ds_read_b128 v[168:171], v0 offset:3072
	v_lshl_add_u64 v[176:177], s[2:3], 0, v[158:159]
	s_add_i32 m0, s27, 0xc000
	ds_read_b128 v[172:175], v205
	ds_read_b128 v[206:209], v205 offset:1024
	ds_read_b128 v[210:213], v205 offset:2048
	ds_read_b128 v[214:217], v205 offset:3072
	ds_read_b128 v[218:221], v205 offset:4096
	ds_read_b128 v[222:225], v205 offset:5120
	ds_read_b128 v[226:229], v205 offset:6144
	ds_read_b128 v[236:239], v205 offset:7168
	global_load_lds_dwordx4 v[176:177], off
	v_lshl_add_u64 v[176:177], s[2:3], 0, v[156:157]
	s_add_i32 m0, s27, 0xe000
	s_nop 0
	global_load_lds_dwordx4 v[176:177], off
	s_waitcnt vmcnt(8)
	s_waitcnt lgkmcnt(0)
	s_barrier
	s_setprio 1
	s_waitcnt lgkmcnt(0)
	v_mfma_f32_16x16x32_bf16 v[126:129], v[130:133], v[172:175], 0
	v_mfma_f32_16x16x32_bf16 v[118:121], v[138:141], v[172:175], 0
	v_mfma_f32_16x16x32_bf16 v[110:113], v[130:133], v[210:213], 0
	v_mfma_f32_16x16x32_bf16 v[102:105], v[138:141], v[210:213], 0
	v_mfma_f32_16x16x32_bf16 v[94:97], v[130:133], v[218:221], 0
	v_mfma_f32_16x16x32_bf16 v[86:89], v[138:141], v[218:221], 0
	v_mfma_f32_16x16x32_bf16 v[78:81], v[130:133], v[226:229], 0
	v_mfma_f32_16x16x32_bf16 v[70:73], v[138:141], v[226:229], 0
	v_mfma_f32_16x16x32_bf16 v[126:129], v[134:137], v[206:209], v[126:129]
	v_mfma_f32_16x16x32_bf16 v[118:121], v[142:145], v[206:209], v[118:121]
	v_mfma_f32_16x16x32_bf16 v[110:113], v[134:137], v[214:217], v[110:113]
	v_mfma_f32_16x16x32_bf16 v[102:105], v[142:145], v[214:217], v[102:105]
	v_mfma_f32_16x16x32_bf16 v[94:97], v[134:137], v[222:225], v[94:97]
	v_mfma_f32_16x16x32_bf16 v[86:89], v[142:145], v[222:225], v[86:89]
	v_mfma_f32_16x16x32_bf16 v[78:81], v[134:137], v[236:239], v[78:81]
	v_mfma_f32_16x16x32_bf16 v[70:73], v[142:145], v[236:239], v[70:73]
	v_mfma_f32_16x16x32_bf16 v[122:125], v[146:149], v[172:175], 0
	v_mfma_f32_16x16x32_bf16 v[114:117], v[164:167], v[172:175], 0
	v_mfma_f32_16x16x32_bf16 v[106:109], v[146:149], v[210:213], 0
	v_mfma_f32_16x16x32_bf16 v[98:101], v[164:167], v[210:213], 0
	v_mfma_f32_16x16x32_bf16 v[90:93], v[146:149], v[218:221], 0
	v_mfma_f32_16x16x32_bf16 v[82:85], v[164:167], v[218:221], 0
	v_mfma_f32_16x16x32_bf16 v[74:77], v[146:149], v[226:229], 0
	v_mfma_f32_16x16x32_bf16 v[66:69], v[164:167], v[226:229], 0
	v_mfma_f32_16x16x32_bf16 v[122:125], v[160:163], v[206:209], v[122:125]
	v_mfma_f32_16x16x32_bf16 v[114:117], v[168:171], v[206:209], v[114:117]
	v_mfma_f32_16x16x32_bf16 v[106:109], v[160:163], v[214:217], v[106:109]
	v_mfma_f32_16x16x32_bf16 v[98:101], v[168:171], v[214:217], v[98:101]
	v_mfma_f32_16x16x32_bf16 v[90:93], v[160:163], v[222:225], v[90:93]
	v_mfma_f32_16x16x32_bf16 v[82:85], v[168:171], v[222:225], v[82:85]
	v_mfma_f32_16x16x32_bf16 v[74:77], v[160:163], v[236:239], v[74:77]
	v_mfma_f32_16x16x32_bf16 v[66:69], v[168:171], v[236:239], v[66:69]
	s_setprio 0
	s_barrier
	s_add_i32 s29, s29, s44
	v_lshl_add_u64 v[176:177], s[30:31], 0, v[152:153]
	s_mov_b32 m0, s29
	ds_read_b128 v[172:175], v205 offset:16384
	ds_read_b128 v[206:209], v205 offset:17408
	ds_read_b128 v[210:213], v205 offset:18432
	ds_read_b128 v[214:217], v205 offset:19456
	ds_read_b128 v[218:221], v205 offset:20480
	ds_read_b128 v[222:225], v205 offset:21504
	ds_read_b128 v[226:229], v205 offset:22528
	ds_read_b128 v[236:239], v205 offset:23552
	global_load_lds_dwordx4 v[176:177], off
	s_add_i32 m0, s29, 0x2000
	v_lshl_add_u64 v[230:231], s[30:31], 0, v[154:155]
	s_add_u32 s30, s30, s12
	s_addc_u32 s31, s31, s13
	s_add_i32 s21, s21, s44
	global_load_lds_dwordx4 v[230:231], off
	v_lshl_add_u64 v[240:241], s[30:31], 0, v[152:153]
	s_mov_b32 m0, s21
	v_lshl_add_u64 v[242:243], s[30:31], 0, v[154:155]
	global_load_lds_dwordx4 v[240:241], off
	s_add_i32 m0, s21, 0x2000
	v_lshl_add_u64 v[244:245], s[4:5], 0, v[152:153]
	global_load_lds_dwordx4 v[242:243], off
	s_mov_b32 m0, s27
	v_lshl_add_u64 v[246:247], s[4:5], 0, v[154:155]
	global_load_lds_dwordx4 v[244:245], off
	s_mov_b32 m0, s45
	s_nop 0
	global_load_lds_dwordx4 v[246:247], off
	s_waitcnt vmcnt(8)
	s_waitcnt lgkmcnt(0)
	s_barrier
	s_setprio 1
	s_waitcnt lgkmcnt(0)
	v_mfma_f32_16x16x32_bf16 v[62:65], v[130:133], v[172:175], 0
	v_mfma_f32_16x16x32_bf16 v[54:57], v[138:141], v[172:175], 0
	v_mfma_f32_16x16x32_bf16 v[46:49], v[130:133], v[210:213], 0
	v_mfma_f32_16x16x32_bf16 v[38:41], v[138:141], v[210:213], 0
	v_mfma_f32_16x16x32_bf16 v[30:33], v[130:133], v[218:221], 0
	v_mfma_f32_16x16x32_bf16 v[22:25], v[138:141], v[218:221], 0
	v_mfma_f32_16x16x32_bf16 v[14:17], v[130:133], v[226:229], 0
	v_mfma_f32_16x16x32_bf16 v[6:9], v[138:141], v[226:229], 0
	v_mfma_f32_16x16x32_bf16 v[62:65], v[134:137], v[206:209], v[62:65]
	v_mfma_f32_16x16x32_bf16 v[54:57], v[142:145], v[206:209], v[54:57]
	v_mfma_f32_16x16x32_bf16 v[46:49], v[134:137], v[214:217], v[46:49]
	v_mfma_f32_16x16x32_bf16 v[38:41], v[142:145], v[214:217], v[38:41]
	v_mfma_f32_16x16x32_bf16 v[30:33], v[134:137], v[222:225], v[30:33]
	v_mfma_f32_16x16x32_bf16 v[22:25], v[142:145], v[222:225], v[22:25]
	v_mfma_f32_16x16x32_bf16 v[14:17], v[134:137], v[236:239], v[14:17]
	v_mfma_f32_16x16x32_bf16 v[6:9], v[142:145], v[236:239], v[6:9]
	v_mfma_f32_16x16x32_bf16 v[58:61], v[146:149], v[172:175], 0
	v_mfma_f32_16x16x32_bf16 v[50:53], v[164:167], v[172:175], 0
	v_mfma_f32_16x16x32_bf16 v[42:45], v[146:149], v[210:213], 0
	v_mfma_f32_16x16x32_bf16 v[34:37], v[164:167], v[210:213], 0
	v_mfma_f32_16x16x32_bf16 v[26:29], v[146:149], v[218:221], 0
	v_mfma_f32_16x16x32_bf16 v[18:21], v[164:167], v[218:221], 0
	v_mfma_f32_16x16x32_bf16 v[10:13], v[146:149], v[226:229], 0
	v_mfma_f32_16x16x32_bf16 v[2:5], v[164:167], v[226:229], 0
	v_mfma_f32_16x16x32_bf16 v[58:61], v[160:163], v[206:209], v[58:61]
	v_mfma_f32_16x16x32_bf16 v[50:53], v[168:171], v[206:209], v[50:53]
	v_mfma_f32_16x16x32_bf16 v[42:45], v[160:163], v[214:217], v[42:45]
	v_mfma_f32_16x16x32_bf16 v[34:37], v[168:171], v[214:217], v[34:37]
	v_mfma_f32_16x16x32_bf16 v[26:29], v[160:163], v[222:225], v[26:29]
	v_mfma_f32_16x16x32_bf16 v[18:21], v[168:171], v[222:225], v[18:21]
	v_mfma_f32_16x16x32_bf16 v[10:13], v[160:163], v[236:239], v[10:13]
	v_mfma_f32_16x16x32_bf16 v[2:5], v[168:171], v[236:239], v[2:5]
	s_setprio 0
	s_barrier
	s_add_i32 s21, 0, 0x18000
	v_add_u32_e32 v0, s21, v204
	s_add_i32 s29, 0, 0x1c000
	ds_read_b128 v[130:133], v0
	ds_read_b128 v[134:137], v0 offset:1024
	ds_read_b128 v[138:141], v0 offset:2048
	ds_read_b128 v[142:145], v0 offset:3072
	v_add_u32_e32 v0, s29, v204
	ds_read_b128 v[146:149], v0
	ds_read_b128 v[160:163], v0 offset:1024
	ds_read_b128 v[164:167], v0 offset:2048
	ds_read_b128 v[168:171], v0 offset:3072
	s_add_u32 s4, s4, s12
	s_addc_u32 s5, s5, s13
	s_mov_b32 m0, s46
	v_lshl_add_u64 v[248:249], s[4:5], 0, v[152:153]
	ds_read_b128 v[172:175], v205 offset:32768
	ds_read_b128 v[206:209], v205 offset:33792
	ds_read_b128 v[210:213], v205 offset:34816
	ds_read_b128 v[214:217], v205 offset:35840
	ds_read_b128 v[218:221], v205 offset:36864
	ds_read_b128 v[222:225], v205 offset:37888
	ds_read_b128 v[226:229], v205 offset:38912
	ds_read_b128 v[236:239], v205 offset:39936
	global_load_lds_dwordx4 v[248:249], off
	v_lshl_add_u64 v[248:249], s[4:5], 0, v[154:155]
	s_mov_b32 m0, s47
	s_nop 0
	global_load_lds_dwordx4 v[248:249], off
	s_waitcnt vmcnt(8)
	s_waitcnt lgkmcnt(0)
	s_barrier
	s_setprio 1
	s_waitcnt lgkmcnt(0)
	v_mfma_f32_16x16x32_bf16 v[126:129], v[130:133], v[172:175], v[126:129]
	v_mfma_f32_16x16x32_bf16 v[118:121], v[138:141], v[172:175], v[118:121]
	v_mfma_f32_16x16x32_bf16 v[110:113], v[130:133], v[210:213], v[110:113]
	v_mfma_f32_16x16x32_bf16 v[102:105], v[138:141], v[210:213], v[102:105]
	v_mfma_f32_16x16x32_bf16 v[94:97], v[130:133], v[218:221], v[94:97]
	v_mfma_f32_16x16x32_bf16 v[86:89], v[138:141], v[218:221], v[86:89]
	v_mfma_f32_16x16x32_bf16 v[78:81], v[130:133], v[226:229], v[78:81]
	v_mfma_f32_16x16x32_bf16 v[70:73], v[138:141], v[226:229], v[70:73]
	v_mfma_f32_16x16x32_bf16 v[126:129], v[134:137], v[206:209], v[126:129]
	v_mfma_f32_16x16x32_bf16 v[118:121], v[142:145], v[206:209], v[118:121]
	v_mfma_f32_16x16x32_bf16 v[110:113], v[134:137], v[214:217], v[110:113]
	v_mfma_f32_16x16x32_bf16 v[102:105], v[142:145], v[214:217], v[102:105]
	v_mfma_f32_16x16x32_bf16 v[94:97], v[134:137], v[222:225], v[94:97]
	v_mfma_f32_16x16x32_bf16 v[86:89], v[142:145], v[222:225], v[86:89]
	v_mfma_f32_16x16x32_bf16 v[78:81], v[134:137], v[236:239], v[78:81]
	v_mfma_f32_16x16x32_bf16 v[70:73], v[142:145], v[236:239], v[70:73]
	v_mfma_f32_16x16x32_bf16 v[122:125], v[146:149], v[172:175], v[122:125]
	v_mfma_f32_16x16x32_bf16 v[114:117], v[164:167], v[172:175], v[114:117]
	v_mfma_f32_16x16x32_bf16 v[106:109], v[146:149], v[210:213], v[106:109]
	v_mfma_f32_16x16x32_bf16 v[98:101], v[164:167], v[210:213], v[98:101]
	v_mfma_f32_16x16x32_bf16 v[90:93], v[146:149], v[218:221], v[90:93]
	v_mfma_f32_16x16x32_bf16 v[82:85], v[164:167], v[218:221], v[82:85]
	v_mfma_f32_16x16x32_bf16 v[74:77], v[146:149], v[226:229], v[74:77]
	v_mfma_f32_16x16x32_bf16 v[66:69], v[164:167], v[226:229], v[66:69]
	v_mfma_f32_16x16x32_bf16 v[122:125], v[160:163], v[206:209], v[122:125]
	v_mfma_f32_16x16x32_bf16 v[114:117], v[168:171], v[206:209], v[114:117]
	v_mfma_f32_16x16x32_bf16 v[106:109], v[160:163], v[214:217], v[106:109]
	v_mfma_f32_16x16x32_bf16 v[98:101], v[168:171], v[214:217], v[98:101]
	v_mfma_f32_16x16x32_bf16 v[90:93], v[160:163], v[222:225], v[90:93]
	v_mfma_f32_16x16x32_bf16 v[82:85], v[168:171], v[222:225], v[82:85]
	v_mfma_f32_16x16x32_bf16 v[74:77], v[160:163], v[236:239], v[74:77]
	v_mfma_f32_16x16x32_bf16 v[66:69], v[168:171], v[236:239], v[66:69]
	s_setprio 0
	s_barrier
	s_add_i32 s4, s21, s44
	v_lshl_add_u64 v[176:177], v[176:177], 0, s[92:93]
	s_mov_b32 m0, s4
	ds_read_b128 v[172:175], v205 offset:49152
	ds_read_b128 v[206:209], v205 offset:50176
	ds_read_b128 v[210:213], v205 offset:51200
	ds_read_b128 v[214:217], v205 offset:52224
	ds_read_b128 v[218:221], v205 offset:53248
	ds_read_b128 v[222:225], v205 offset:54272
	ds_read_b128 v[226:229], v205 offset:55296
	ds_read_b128 v[236:239], v205 offset:56320
	global_load_lds_dwordx4 v[176:177], off
	v_lshl_add_u64 v[176:177], v[230:231], 0, s[92:93]
	s_add_i32 m0, s4, 0x2000
	s_add_i32 s4, s29, s44
	global_load_lds_dwordx4 v[176:177], off
	v_lshl_add_u64 v[176:177], v[240:241], 0, s[92:93]
	s_mov_b32 m0, s4
	s_nop 0
	global_load_lds_dwordx4 v[176:177], off
	v_lshl_add_u64 v[176:177], v[242:243], 0, s[92:93]
	s_add_i32 m0, s4, 0x2000
	s_nop 0
	global_load_lds_dwordx4 v[176:177], off
	v_lshl_add_u64 v[176:177], v[244:245], 0, s[92:93]
	s_mov_b32 m0, s48
	s_nop 0
	global_load_lds_dwordx4 v[176:177], off
	v_lshl_add_u64 v[176:177], v[246:247], 0, s[92:93]
	s_mov_b32 m0, s49
	s_nop 0
	global_load_lds_dwordx4 v[176:177], off
	s_waitcnt vmcnt(8)
	s_waitcnt lgkmcnt(0)
	s_barrier
	s_setprio 1
	s_waitcnt lgkmcnt(0)
	v_mfma_f32_16x16x32_bf16 v[62:65], v[130:133], v[172:175], v[62:65]
	v_mfma_f32_16x16x32_bf16 v[54:57], v[138:141], v[172:175], v[54:57]
	v_mfma_f32_16x16x32_bf16 v[46:49], v[130:133], v[210:213], v[46:49]
	v_mfma_f32_16x16x32_bf16 v[38:41], v[138:141], v[210:213], v[38:41]
	v_mfma_f32_16x16x32_bf16 v[30:33], v[130:133], v[218:221], v[30:33]
	v_mfma_f32_16x16x32_bf16 v[22:25], v[138:141], v[218:221], v[22:25]
	v_mfma_f32_16x16x32_bf16 v[14:17], v[130:133], v[226:229], v[14:17]
	v_mfma_f32_16x16x32_bf16 v[6:9], v[138:141], v[226:229], v[6:9]
	v_mfma_f32_16x16x32_bf16 v[62:65], v[134:137], v[206:209], v[62:65]
	v_mfma_f32_16x16x32_bf16 v[54:57], v[142:145], v[206:209], v[54:57]
	v_mfma_f32_16x16x32_bf16 v[46:49], v[134:137], v[214:217], v[46:49]
	v_mfma_f32_16x16x32_bf16 v[38:41], v[142:145], v[214:217], v[38:41]
	v_mfma_f32_16x16x32_bf16 v[30:33], v[134:137], v[222:225], v[30:33]
	v_mfma_f32_16x16x32_bf16 v[22:25], v[142:145], v[222:225], v[22:25]
	v_mfma_f32_16x16x32_bf16 v[14:17], v[134:137], v[236:239], v[14:17]
	v_mfma_f32_16x16x32_bf16 v[6:9], v[142:145], v[236:239], v[6:9]
	v_mfma_f32_16x16x32_bf16 v[58:61], v[146:149], v[172:175], v[58:61]
	v_mfma_f32_16x16x32_bf16 v[50:53], v[164:167], v[172:175], v[50:53]
	v_mfma_f32_16x16x32_bf16 v[42:45], v[146:149], v[210:213], v[42:45]
	v_mfma_f32_16x16x32_bf16 v[34:37], v[164:167], v[210:213], v[34:37]
	v_mfma_f32_16x16x32_bf16 v[26:29], v[146:149], v[218:221], v[26:29]
	v_mfma_f32_16x16x32_bf16 v[18:21], v[164:167], v[218:221], v[18:21]
	v_mfma_f32_16x16x32_bf16 v[10:13], v[146:149], v[226:229], v[10:13]
	v_mfma_f32_16x16x32_bf16 v[2:5], v[164:167], v[226:229], v[2:5]
	v_mfma_f32_16x16x32_bf16 v[58:61], v[160:163], v[206:209], v[58:61]
	v_mfma_f32_16x16x32_bf16 v[50:53], v[168:171], v[206:209], v[50:53]
	v_mfma_f32_16x16x32_bf16 v[42:45], v[160:163], v[214:217], v[42:45]
	v_mfma_f32_16x16x32_bf16 v[34:37], v[168:171], v[214:217], v[34:37]
	v_mfma_f32_16x16x32_bf16 v[26:29], v[160:163], v[222:225], v[26:29]
	v_mfma_f32_16x16x32_bf16 v[18:21], v[168:171], v[222:225], v[18:21]
	v_mfma_f32_16x16x32_bf16 v[10:13], v[160:163], v[236:239], v[10:13]
	v_mfma_f32_16x16x32_bf16 v[2:5], v[168:171], v[236:239], v[2:5]
	s_setprio 0
	s_barrier
	s_add_u32 s7, s7, 0x100
	s_addc_u32 s8, s8, 0
	s_add_u32 s2, s2, 0x100
	s_addc_u32 s3, s3, 0
	s_cmp_ge_i32 s9, s28
	s_mov_b32 s4, s9
	s_cbranch_scc0 .LBB0_811
	s_branch .Lk_exit
.LBB0_811:
	s_add_i32 s9, s4, 2
	s_add_u32 s21, s2, 0x80
	s_addc_u32 s5, s3, 0
	s_add_i32 s29, 0, 0x10000
	s_cmp_eq_u32 s6, s4
	s_cselect_b32 s5, s23, s5
	s_cselect_b32 s4, s22, s21
	v_add_u32_e32 v0, s29, v204
	s_cselect_b32 s31, s25, s8
	s_cselect_b32 s30, s24, s7
	s_add_i32 s21, 0, 0x14000
	ds_read_b128 v[130:133], v0
	ds_read_b128 v[134:137], v0 offset:1024
	ds_read_b128 v[138:141], v0 offset:2048
	ds_read_b128 v[142:145], v0 offset:3072
	v_add_u32_e32 v0, s21, v204
	ds_read_b128 v[146:149], v0
	ds_read_b128 v[160:163], v0 offset:1024
	ds_read_b128 v[164:167], v0 offset:2048
	ds_read_b128 v[168:171], v0 offset:3072
	v_lshl_add_u64 v[176:177], s[2:3], 0, v[158:159]
	s_add_i32 m0, s27, 0xc000
	ds_read_b128 v[172:175], v205
	ds_read_b128 v[206:209], v205 offset:1024
	ds_read_b128 v[210:213], v205 offset:2048
	ds_read_b128 v[214:217], v205 offset:3072
	ds_read_b128 v[218:221], v205 offset:4096
	ds_read_b128 v[222:225], v205 offset:5120
	ds_read_b128 v[226:229], v205 offset:6144
	ds_read_b128 v[236:239], v205 offset:7168
	global_load_lds_dwordx4 v[176:177], off
	v_lshl_add_u64 v[176:177], s[2:3], 0, v[156:157]
	s_add_i32 m0, s27, 0xe000
	s_nop 0
	global_load_lds_dwordx4 v[176:177], off
	s_waitcnt vmcnt(8)
	s_waitcnt lgkmcnt(0)
	s_barrier
	s_setprio 1
	s_waitcnt lgkmcnt(0)
	v_mfma_f32_16x16x32_bf16 v[126:129], v[130:133], v[172:175], v[126:129]
	v_mfma_f32_16x16x32_bf16 v[118:121], v[138:141], v[172:175], v[118:121]
	v_mfma_f32_16x16x32_bf16 v[110:113], v[130:133], v[210:213], v[110:113]
	v_mfma_f32_16x16x32_bf16 v[102:105], v[138:141], v[210:213], v[102:105]
	v_mfma_f32_16x16x32_bf16 v[94:97], v[130:133], v[218:221], v[94:97]
	v_mfma_f32_16x16x32_bf16 v[86:89], v[138:141], v[218:221], v[86:89]
	v_mfma_f32_16x16x32_bf16 v[78:81], v[130:133], v[226:229], v[78:81]
	v_mfma_f32_16x16x32_bf16 v[70:73], v[138:141], v[226:229], v[70:73]
	v_mfma_f32_16x16x32_bf16 v[126:129], v[134:137], v[206:209], v[126:129]
	v_mfma_f32_16x16x32_bf16 v[118:121], v[142:145], v[206:209], v[118:121]
	v_mfma_f32_16x16x32_bf16 v[110:113], v[134:137], v[214:217], v[110:113]
	v_mfma_f32_16x16x32_bf16 v[102:105], v[142:145], v[214:217], v[102:105]
	v_mfma_f32_16x16x32_bf16 v[94:97], v[134:137], v[222:225], v[94:97]
	v_mfma_f32_16x16x32_bf16 v[86:89], v[142:145], v[222:225], v[86:89]
	v_mfma_f32_16x16x32_bf16 v[78:81], v[134:137], v[236:239], v[78:81]
	v_mfma_f32_16x16x32_bf16 v[70:73], v[142:145], v[236:239], v[70:73]
	v_mfma_f32_16x16x32_bf16 v[122:125], v[146:149], v[172:175], v[122:125]
	v_mfma_f32_16x16x32_bf16 v[114:117], v[164:167], v[172:175], v[114:117]
	v_mfma_f32_16x16x32_bf16 v[106:109], v[146:149], v[210:213], v[106:109]
	v_mfma_f32_16x16x32_bf16 v[98:101], v[164:167], v[210:213], v[98:101]
	v_mfma_f32_16x16x32_bf16 v[90:93], v[146:149], v[218:221], v[90:93]
	v_mfma_f32_16x16x32_bf16 v[82:85], v[164:167], v[218:221], v[82:85]
	v_mfma_f32_16x16x32_bf16 v[74:77], v[146:149], v[226:229], v[74:77]
	v_mfma_f32_16x16x32_bf16 v[66:69], v[164:167], v[226:229], v[66:69]
	v_mfma_f32_16x16x32_bf16 v[122:125], v[160:163], v[206:209], v[122:125]
	v_mfma_f32_16x16x32_bf16 v[114:117], v[168:171], v[206:209], v[114:117]
	v_mfma_f32_16x16x32_bf16 v[106:109], v[160:163], v[214:217], v[106:109]
	v_mfma_f32_16x16x32_bf16 v[98:101], v[168:171], v[214:217], v[98:101]
	v_mfma_f32_16x16x32_bf16 v[90:93], v[160:163], v[222:225], v[90:93]
	v_mfma_f32_16x16x32_bf16 v[82:85], v[168:171], v[222:225], v[82:85]
	v_mfma_f32_16x16x32_bf16 v[74:77], v[160:163], v[236:239], v[74:77]
	v_mfma_f32_16x16x32_bf16 v[66:69], v[168:171], v[236:239], v[66:69]
	s_setprio 0
	s_barrier
	s_add_i32 s29, s29, s44
	v_lshl_add_u64 v[176:177], s[30:31], 0, v[152:153]
	s_mov_b32 m0, s29
	ds_read_b128 v[172:175], v205 offset:16384
	ds_read_b128 v[206:209], v205 offset:17408
	ds_read_b128 v[210:213], v205 offset:18432
	ds_read_b128 v[214:217], v205 offset:19456
	ds_read_b128 v[218:221], v205 offset:20480
	ds_read_b128 v[222:225], v205 offset:21504
	ds_read_b128 v[226:229], v205 offset:22528
	ds_read_b128 v[236:239], v205 offset:23552
	global_load_lds_dwordx4 v[176:177], off
	s_add_i32 m0, s29, 0x2000
	v_lshl_add_u64 v[230:231], s[30:31], 0, v[154:155]
	s_add_u32 s30, s30, s12
	s_addc_u32 s31, s31, s13
	s_add_i32 s21, s21, s44
	global_load_lds_dwordx4 v[230:231], off
	v_lshl_add_u64 v[240:241], s[30:31], 0, v[152:153]
	s_mov_b32 m0, s21
	v_lshl_add_u64 v[242:243], s[30:31], 0, v[154:155]
	global_load_lds_dwordx4 v[240:241], off
	s_add_i32 m0, s21, 0x2000
	v_lshl_add_u64 v[244:245], s[4:5], 0, v[152:153]
	global_load_lds_dwordx4 v[242:243], off
	s_mov_b32 m0, s27
	v_lshl_add_u64 v[246:247], s[4:5], 0, v[154:155]
	global_load_lds_dwordx4 v[244:245], off
	s_mov_b32 m0, s45
	s_nop 0
	global_load_lds_dwordx4 v[246:247], off
	s_waitcnt vmcnt(8)
	s_waitcnt lgkmcnt(0)
	s_barrier
	s_setprio 1
	s_waitcnt lgkmcnt(0)
	v_mfma_f32_16x16x32_bf16 v[62:65], v[130:133], v[172:175], v[62:65]
	v_mfma_f32_16x16x32_bf16 v[54:57], v[138:141], v[172:175], v[54:57]
	v_mfma_f32_16x16x32_bf16 v[46:49], v[130:133], v[210:213], v[46:49]
	v_mfma_f32_16x16x32_bf16 v[38:41], v[138:141], v[210:213], v[38:41]
	v_mfma_f32_16x16x32_bf16 v[30:33], v[130:133], v[218:221], v[30:33]
	v_mfma_f32_16x16x32_bf16 v[22:25], v[138:141], v[218:221], v[22:25]
	v_mfma_f32_16x16x32_bf16 v[14:17], v[130:133], v[226:229], v[14:17]
	v_mfma_f32_16x16x32_bf16 v[6:9], v[138:141], v[226:229], v[6:9]
	v_mfma_f32_16x16x32_bf16 v[62:65], v[134:137], v[206:209], v[62:65]
	v_mfma_f32_16x16x32_bf16 v[54:57], v[142:145], v[206:209], v[54:57]
	v_mfma_f32_16x16x32_bf16 v[46:49], v[134:137], v[214:217], v[46:49]
	v_mfma_f32_16x16x32_bf16 v[38:41], v[142:145], v[214:217], v[38:41]
	v_mfma_f32_16x16x32_bf16 v[30:33], v[134:137], v[222:225], v[30:33]
	v_mfma_f32_16x16x32_bf16 v[22:25], v[142:145], v[222:225], v[22:25]
	v_mfma_f32_16x16x32_bf16 v[14:17], v[134:137], v[236:239], v[14:17]
	v_mfma_f32_16x16x32_bf16 v[6:9], v[142:145], v[236:239], v[6:9]
	v_mfma_f32_16x16x32_bf16 v[58:61], v[146:149], v[172:175], v[58:61]
	v_mfma_f32_16x16x32_bf16 v[50:53], v[164:167], v[172:175], v[50:53]
	v_mfma_f32_16x16x32_bf16 v[42:45], v[146:149], v[210:213], v[42:45]
	v_mfma_f32_16x16x32_bf16 v[34:37], v[164:167], v[210:213], v[34:37]
	v_mfma_f32_16x16x32_bf16 v[26:29], v[146:149], v[218:221], v[26:29]
	v_mfma_f32_16x16x32_bf16 v[18:21], v[164:167], v[218:221], v[18:21]
	v_mfma_f32_16x16x32_bf16 v[10:13], v[146:149], v[226:229], v[10:13]
	v_mfma_f32_16x16x32_bf16 v[2:5], v[164:167], v[226:229], v[2:5]
	v_mfma_f32_16x16x32_bf16 v[58:61], v[160:163], v[206:209], v[58:61]
	v_mfma_f32_16x16x32_bf16 v[50:53], v[168:171], v[206:209], v[50:53]
	v_mfma_f32_16x16x32_bf16 v[42:45], v[160:163], v[214:217], v[42:45]
	v_mfma_f32_16x16x32_bf16 v[34:37], v[168:171], v[214:217], v[34:37]
	v_mfma_f32_16x16x32_bf16 v[26:29], v[160:163], v[222:225], v[26:29]
	v_mfma_f32_16x16x32_bf16 v[18:21], v[168:171], v[222:225], v[18:21]
	v_mfma_f32_16x16x32_bf16 v[10:13], v[160:163], v[236:239], v[10:13]
	v_mfma_f32_16x16x32_bf16 v[2:5], v[168:171], v[236:239], v[2:5]
	s_setprio 0
	s_barrier
	s_add_i32 s21, 0, 0x18000
	v_add_u32_e32 v0, s21, v204
	s_add_i32 s29, 0, 0x1c000
	ds_read_b128 v[130:133], v0
	ds_read_b128 v[134:137], v0 offset:1024
	ds_read_b128 v[138:141], v0 offset:2048
	ds_read_b128 v[142:145], v0 offset:3072
	v_add_u32_e32 v0, s29, v204
	ds_read_b128 v[146:149], v0
	ds_read_b128 v[160:163], v0 offset:1024
	ds_read_b128 v[164:167], v0 offset:2048
	ds_read_b128 v[168:171], v0 offset:3072
	s_add_u32 s4, s4, s12
	s_addc_u32 s5, s5, s13
	s_mov_b32 m0, s46
	v_lshl_add_u64 v[248:249], s[4:5], 0, v[152:153]
	ds_read_b128 v[172:175], v205 offset:32768
	ds_read_b128 v[206:209], v205 offset:33792
	ds_read_b128 v[210:213], v205 offset:34816
	ds_read_b128 v[214:217], v205 offset:35840
	ds_read_b128 v[218:221], v205 offset:36864
	ds_read_b128 v[222:225], v205 offset:37888
	ds_read_b128 v[226:229], v205 offset:38912
	ds_read_b128 v[236:239], v205 offset:39936
	global_load_lds_dwordx4 v[248:249], off
	v_lshl_add_u64 v[248:249], s[4:5], 0, v[154:155]
	s_mov_b32 m0, s47
	s_nop 0
	global_load_lds_dwordx4 v[248:249], off
	s_waitcnt vmcnt(8)
	s_waitcnt lgkmcnt(0)
	s_barrier
	s_setprio 1
	s_waitcnt lgkmcnt(0)
	v_mfma_f32_16x16x32_bf16 v[126:129], v[130:133], v[172:175], v[126:129]
	v_mfma_f32_16x16x32_bf16 v[118:121], v[138:141], v[172:175], v[118:121]
	v_mfma_f32_16x16x32_bf16 v[110:113], v[130:133], v[210:213], v[110:113]
	v_mfma_f32_16x16x32_bf16 v[102:105], v[138:141], v[210:213], v[102:105]
	v_mfma_f32_16x16x32_bf16 v[94:97], v[130:133], v[218:221], v[94:97]
	v_mfma_f32_16x16x32_bf16 v[86:89], v[138:141], v[218:221], v[86:89]
	v_mfma_f32_16x16x32_bf16 v[78:81], v[130:133], v[226:229], v[78:81]
	v_mfma_f32_16x16x32_bf16 v[70:73], v[138:141], v[226:229], v[70:73]
	v_mfma_f32_16x16x32_bf16 v[126:129], v[134:137], v[206:209], v[126:129]
	v_mfma_f32_16x16x32_bf16 v[118:121], v[142:145], v[206:209], v[118:121]
	v_mfma_f32_16x16x32_bf16 v[110:113], v[134:137], v[214:217], v[110:113]
	v_mfma_f32_16x16x32_bf16 v[102:105], v[142:145], v[214:217], v[102:105]
	v_mfma_f32_16x16x32_bf16 v[94:97], v[134:137], v[222:225], v[94:97]
	v_mfma_f32_16x16x32_bf16 v[86:89], v[142:145], v[222:225], v[86:89]
	v_mfma_f32_16x16x32_bf16 v[78:81], v[134:137], v[236:239], v[78:81]
	v_mfma_f32_16x16x32_bf16 v[70:73], v[142:145], v[236:239], v[70:73]
	v_mfma_f32_16x16x32_bf16 v[122:125], v[146:149], v[172:175], v[122:125]
	v_mfma_f32_16x16x32_bf16 v[114:117], v[164:167], v[172:175], v[114:117]
	v_mfma_f32_16x16x32_bf16 v[106:109], v[146:149], v[210:213], v[106:109]
	v_mfma_f32_16x16x32_bf16 v[98:101], v[164:167], v[210:213], v[98:101]
	v_mfma_f32_16x16x32_bf16 v[90:93], v[146:149], v[218:221], v[90:93]
	v_mfma_f32_16x16x32_bf16 v[82:85], v[164:167], v[218:221], v[82:85]
	v_mfma_f32_16x16x32_bf16 v[74:77], v[146:149], v[226:229], v[74:77]
	v_mfma_f32_16x16x32_bf16 v[66:69], v[164:167], v[226:229], v[66:69]
	v_mfma_f32_16x16x32_bf16 v[122:125], v[160:163], v[206:209], v[122:125]
	v_mfma_f32_16x16x32_bf16 v[114:117], v[168:171], v[206:209], v[114:117]
	v_mfma_f32_16x16x32_bf16 v[106:109], v[160:163], v[214:217], v[106:109]
	v_mfma_f32_16x16x32_bf16 v[98:101], v[168:171], v[214:217], v[98:101]
	v_mfma_f32_16x16x32_bf16 v[90:93], v[160:163], v[222:225], v[90:93]
	v_mfma_f32_16x16x32_bf16 v[82:85], v[168:171], v[222:225], v[82:85]
	v_mfma_f32_16x16x32_bf16 v[74:77], v[160:163], v[236:239], v[74:77]
	v_mfma_f32_16x16x32_bf16 v[66:69], v[168:171], v[236:239], v[66:69]
	s_setprio 0
	s_barrier
	s_add_i32 s4, s21, s44
	v_lshl_add_u64 v[176:177], v[176:177], 0, s[92:93]
	s_mov_b32 m0, s4
	ds_read_b128 v[172:175], v205 offset:49152
	ds_read_b128 v[206:209], v205 offset:50176
	ds_read_b128 v[210:213], v205 offset:51200
	ds_read_b128 v[214:217], v205 offset:52224
	ds_read_b128 v[218:221], v205 offset:53248
	ds_read_b128 v[222:225], v205 offset:54272
	ds_read_b128 v[226:229], v205 offset:55296
	ds_read_b128 v[236:239], v205 offset:56320
	global_load_lds_dwordx4 v[176:177], off
	v_lshl_add_u64 v[176:177], v[230:231], 0, s[92:93]
	s_add_i32 m0, s4, 0x2000
	s_add_i32 s4, s29, s44
	global_load_lds_dwordx4 v[176:177], off
	v_lshl_add_u64 v[176:177], v[240:241], 0, s[92:93]
	s_mov_b32 m0, s4
	s_nop 0
	global_load_lds_dwordx4 v[176:177], off
	v_lshl_add_u64 v[176:177], v[242:243], 0, s[92:93]
	s_add_i32 m0, s4, 0x2000
	s_nop 0
	global_load_lds_dwordx4 v[176:177], off
	v_lshl_add_u64 v[176:177], v[244:245], 0, s[92:93]
	s_mov_b32 m0, s48
	s_nop 0
	global_load_lds_dwordx4 v[176:177], off
	v_lshl_add_u64 v[176:177], v[246:247], 0, s[92:93]
	s_mov_b32 m0, s49
	s_nop 0
	global_load_lds_dwordx4 v[176:177], off
	s_waitcnt vmcnt(8)
	s_waitcnt lgkmcnt(0)
	s_barrier
	s_setprio 1
	s_waitcnt lgkmcnt(0)
	v_mfma_f32_16x16x32_bf16 v[62:65], v[130:133], v[172:175], v[62:65]
	v_mfma_f32_16x16x32_bf16 v[54:57], v[138:141], v[172:175], v[54:57]
	v_mfma_f32_16x16x32_bf16 v[46:49], v[130:133], v[210:213], v[46:49]
	v_mfma_f32_16x16x32_bf16 v[38:41], v[138:141], v[210:213], v[38:41]
	v_mfma_f32_16x16x32_bf16 v[30:33], v[130:133], v[218:221], v[30:33]
	v_mfma_f32_16x16x32_bf16 v[22:25], v[138:141], v[218:221], v[22:25]
	v_mfma_f32_16x16x32_bf16 v[14:17], v[130:133], v[226:229], v[14:17]
	v_mfma_f32_16x16x32_bf16 v[6:9], v[138:141], v[226:229], v[6:9]
	v_mfma_f32_16x16x32_bf16 v[62:65], v[134:137], v[206:209], v[62:65]
	v_mfma_f32_16x16x32_bf16 v[54:57], v[142:145], v[206:209], v[54:57]
	v_mfma_f32_16x16x32_bf16 v[46:49], v[134:137], v[214:217], v[46:49]
	v_mfma_f32_16x16x32_bf16 v[38:41], v[142:145], v[214:217], v[38:41]
	v_mfma_f32_16x16x32_bf16 v[30:33], v[134:137], v[222:225], v[30:33]
	v_mfma_f32_16x16x32_bf16 v[22:25], v[142:145], v[222:225], v[22:25]
	v_mfma_f32_16x16x32_bf16 v[14:17], v[134:137], v[236:239], v[14:17]
	v_mfma_f32_16x16x32_bf16 v[6:9], v[142:145], v[236:239], v[6:9]
	v_mfma_f32_16x16x32_bf16 v[58:61], v[146:149], v[172:175], v[58:61]
	v_mfma_f32_16x16x32_bf16 v[50:53], v[164:167], v[172:175], v[50:53]
	v_mfma_f32_16x16x32_bf16 v[42:45], v[146:149], v[210:213], v[42:45]
	v_mfma_f32_16x16x32_bf16 v[34:37], v[164:167], v[210:213], v[34:37]
	v_mfma_f32_16x16x32_bf16 v[26:29], v[146:149], v[218:221], v[26:29]
	v_mfma_f32_16x16x32_bf16 v[18:21], v[164:167], v[218:221], v[18:21]
	v_mfma_f32_16x16x32_bf16 v[10:13], v[146:149], v[226:229], v[10:13]
	v_mfma_f32_16x16x32_bf16 v[2:5], v[164:167], v[226:229], v[2:5]
	v_mfma_f32_16x16x32_bf16 v[58:61], v[160:163], v[206:209], v[58:61]
	v_mfma_f32_16x16x32_bf16 v[50:53], v[168:171], v[206:209], v[50:53]
	v_mfma_f32_16x16x32_bf16 v[42:45], v[160:163], v[214:217], v[42:45]
	v_mfma_f32_16x16x32_bf16 v[34:37], v[168:171], v[214:217], v[34:37]
	v_mfma_f32_16x16x32_bf16 v[26:29], v[160:163], v[222:225], v[26:29]
	v_mfma_f32_16x16x32_bf16 v[18:21], v[168:171], v[222:225], v[18:21]
	v_mfma_f32_16x16x32_bf16 v[10:13], v[160:163], v[236:239], v[10:13]
	v_mfma_f32_16x16x32_bf16 v[2:5], v[168:171], v[236:239], v[2:5]
	s_setprio 0
	s_barrier
	s_add_u32 s7, s7, 0x100
	s_addc_u32 s8, s8, 0
	s_add_u32 s2, s2, 0x100
	s_addc_u32 s3, s3, 0
	s_cmp_ge_i32 s9, s28
	s_mov_b32 s4, s9
	s_cbranch_scc0 .LBB0_811
